# v16 + attention common path: S1 from NEGM as C operand (no copy), shorter max chains, cold blocks (mask, max-move, half-tile) out of line
# baseline (speedup 1.0000x reference)
; DI float max_x32(float x) { auto r = __builtin_amdgcn_permlane32_swap(__float_as_uint(x), __float_as_uint(x), false, false); return fmaxf(__uint_as_float(r[0]), __uint_as_float(r[1])); }
; DI void attn_phase(const Params& p, unsigned char* smem) {
;     ...
;             float mx = S[0];
; #pragma unroll
;             for (int i = 1; i < 16; ++i) mx = fmaxf(mx, S[i]);
;             mx = max_x32(mx);
;             if (__any(mx > 8.0f)) {
;                 const float dm = fmaxf(mx, 0.f);
;                 const float alpha = __builtin_amdgcn_exp2f(-dm);
;                 mrun += dm;
;                 lrun *= alpha;
; #pragma unroll
;                 for (int d = 0; d < 4; ++d) O[d] = O[d] * alpha;
; #pragma unroll
;                 for (int i = 0; i < 16; ++i) { S[i] -= dm; NEGM[i] = -mrun; }
;                 if (Spend) {
; #pragma unroll
;                     for (int i = 0; i < 16; ++i) (*Spend)[i] -= dm;
;                 }
;             }
;             float ls = 0.f;
; #pragma unroll
;             for (int i = 0; i < 16; ++i) { const float e = __builtin_amdgcn_exp2f(S[i]); S[i] = e; ls += e; }
;             lrun += ls;
;             P[0] = pack8(S, 0); P[1] = pack8(S, 1);
;         };
;         auto pv_half = [&](const bf16_t* vb, int kh, int dsw, const bf16x8 (&P)[2]) __attribute__((always_inline)) {
; #pragma unroll
;             for (int s2 = 0; s2 < 2; ++s2) {
;                 const int u = kh * 2 + s2;
; #pragma unroll
;                 for (int d = 0; d < 4; ++d) {
;                     const bf16x8 A = *(const bf16x8*)(vb + (d * 32 + l31) * 64 + (((2 * u + hi) ^ dsw) * 8));
;                     O[d] = mfma32(A, P[s2], O[d]);
;                 }
;             }
;         };
;     ...
;                 const bf16_t* kb = sK + buf * 64 * 128;
;                 const bf16_t* vb = sV + buf * 128 * 64;
;                 const bool need_mask = (j == 0) || (kbase + 63 > q0);
;                 const bool act1 = (j >= 1) && (kbase + 32 <= q0 + 31);
;                 const int ksw = l31 & 15, dsw = (l31 >> 1) & 7;
;                 f32x16 S0 = qk_half(kb, 0, ksw);
;                 bf16x8 P[2];
;                 if (act1) {
;                     f32x16 S1 = qk_half(kb, 1, ksw);
;                     softmax_half(S0, &S1, j, 0, kbase, need_mask, P);
;                     pv_half(vb, 0, dsw, P);
.LBB0_1277:
	s_sub_i32 s19, s47, 32
	s_cmp_eq_u32 s18, 0
	s_cselect_b64 s[20:21], -1, 0
	v_cmp_le_i32_e32 vcc, s19, v196
	s_or_b64 s[24:25], s[20:21], vcc
	s_and_saveexec_b64 s[18:19], s[24:25]
	s_cbranch_execz .LBB0_1301
	s_mov_b32 s22, s100
	v_add_u32_e32 v12, s22, v192
	v_lshl_add_u32 v1, v182, 1, v12
	v_lshl_add_u32 v3, v183, 1, v12
	v_lshl_add_u32 v204, v184, 1, v12
	v_lshl_add_u32 v205, v185, 1, v12
	ds_read_b128 v[4:7], v1
	ds_read_b128 v[8:11], v3
	ds_read_b128 v[206:209], v204
	ds_read_b128 v[210:213], v205
	ds_read_b128 v[214:217], v1 offset:8192
	ds_read_b128 v[218:221], v3 offset:8192
	ds_read_b128 v[222:225], v204 offset:8192
	ds_read_b128 v[226:229], v205 offset:8192
	s_add_i32 s49, s22, 0
	s_add_i32 s22, s47, 31
	v_cmp_gt_i32_e32 vcc, s22, v195
	s_or_b64 s[22:23], s[20:21], vcc
	s_xor_b64 s[24:25], s[20:21], -1
	v_cmp_le_i32_e32 vcc, s47, v196
	s_setprio 1
	s_waitcnt lgkmcnt(6)
	v_mfma_f32_32x32x16_bf16 v[96:111], v[4:7], v[128:131], v[80:95]
	s_and_b64 s[24:25], s[24:25], vcc
	v_mfma_f32_32x32x16_bf16 v[96:111], v[8:11], v[132:135], v[96:111]
	s_waitcnt lgkmcnt(4)
	v_mfma_f32_32x32x16_bf16 v[96:111], v[206:209], v[136:139], v[96:111]
	v_mfma_f32_32x32x16_bf16 v[96:111], v[210:213], v[140:143], v[96:111]
	s_setprio 0
	s_and_saveexec_b64 s[26:27], s[24:25]
	s_xor_b64 s[24:25], exec, s[26:27]
	s_cbranch_execz .LBB0_1292
	s_setprio 1
	s_waitcnt lgkmcnt(2)
	v_mfma_f32_32x32x16_bf16 v[112:127], v[214:217], v[128:131], v[80:95]
	v_mfma_f32_32x32x16_bf16 v[112:127], v[218:221], v[132:135], v[112:127]
	s_waitcnt lgkmcnt(0)
	v_mfma_f32_32x32x16_bf16 v[112:127], v[222:225], v[136:139], v[112:127]
	v_mfma_f32_32x32x16_bf16 v[112:127], v[226:229], v[140:143], v[112:127]
	s_setprio 0
	s_and_saveexec_b64 s[26:27], s[22:23]
	s_cbranch_execnz .Lattn_cold_mask0
.LBB0_1283:
	s_or_b64 exec, exec, s[26:27]
	v_max3_f32 v1, v96, v97, v98
	v_max3_f32 v1, v1, v99, v100
	v_max3_f32 v1, v1, v101, v102
	v_max3_f32 v1, v1, v103, v104
	v_max3_f32 v1, v1, v105, v106
	v_max3_f32 v1, v1, v107, v108
	v_max3_f32 v1, v1, v109, v110
	v_max_f32_e32 v1, v1, v111
	v_mov_b32_e32 v3, v1
	s_nop 1
	v_permlane32_swap_b32_e32 v1, v3
	v_max_f32_e32 v1, v1, v3
	v_cmp_lt_f32_e32 vcc, s42, v1
	s_cbranch_vccnz .Lattn_cold_resc0
.LBB0_1285:
	v_lshl_add_u32 v1, v186, 1, s49
	v_exp_f32_e32 v3, v96
	v_lshl_add_u32 v96, v187, 1, v1
	ds_read_b128 v[12:15], v96 offset:32768
	ds_read_b128 v[200:203], v96 offset:36864
	v_exp_f32_e32 v4, v97
	v_exp_f32_e32 v5, v98
	v_exp_f32_e32 v6, v99
	v_exp_f32_e32 v7, v100
	v_exp_f32_e32 v8, v101
	v_exp_f32_e32 v9, v102
	v_exp_f32_e32 v10, v103
	v_cvt_pk_bf16_f32 v98, v3, v4
	v_cvt_pk_bf16_f32 v99, v5, v6
	v_cvt_pk_bf16_f32 v100, v7, v8
	v_cvt_pk_bf16_f32 v101, v9, v10
	v_lshl_add_u32 v199, v188, 1, v1
	v_exp_f32_e32 v11, v104
	s_setprio 1
	s_waitcnt lgkmcnt(0)
	v_mfma_f32_32x32x16_bf16 v[64:79], v[12:15], v[98:101], v[64:79]
	ds_read_b128 v[12:15], v96 offset:40960
	v_exp_f32_e32 v97, v110
	v_mfma_f32_32x32x16_bf16 v[48:63], v[200:203], v[98:101], v[48:63]
	ds_read_b128 v[200:203], v96 offset:45056
	v_exp_f32_e32 v96, v109
	s_waitcnt lgkmcnt(0)
	v_mfma_f32_32x32x16_bf16 v[32:47], v[12:15], v[98:101], v[32:47]
	v_exp_f32_e32 v12, v105
	ds_read_b128 v[102:105], v199 offset:32768
	v_exp_f32_e32 v13, v106
	v_exp_f32_e32 v14, v107
	v_exp_f32_e32 v15, v108
	v_cvt_pk_bf16_f32 v106, v11, v12
	v_cvt_pk_bf16_f32 v107, v13, v14
	v_mfma_f32_32x32x16_bf16 v[16:31], v[200:203], v[98:101], v[16:31]
	ds_read_b128 v[200:203], v199 offset:36864
	v_exp_f32_e32 v98, v111
	v_cvt_pk_bf16_f32 v108, v15, v96
	v_cvt_pk_bf16_f32 v109, v97, v98
	s_waitcnt lgkmcnt(0)
	s_nop 0
	v_mfma_f32_32x32x16_bf16 v[64:79], v[102:105], v[106:109], v[64:79]
	v_mfma_f32_32x32x16_bf16 v[48:63], v[200:203], v[106:109], v[48:63]
	ds_read_b128 v[100:103], v199 offset:40960
	ds_read_b128 v[200:203], v199 offset:45056
	s_waitcnt lgkmcnt(0)
	v_mfma_f32_32x32x16_bf16 v[32:47], v[100:103], v[106:109], v[32:47]
	v_mfma_f32_32x32x16_bf16 v[16:31], v[200:203], v[106:109], v[16:31]
	s_setprio 0
	s_and_saveexec_b64 s[26:27], s[22:23]
	s_cbranch_execnz .Lattn_cold_mask1
; DI float max_x32(float x) { auto r = __builtin_amdgcn_permlane32_swap(__float_as_uint(x), __float_as_uint(x), false, false); return fmaxf(__uint_as_float(r[0]), __uint_as_float(r[1])); }
; DI f32x16 mfma32(bf16x8 a, bf16x8 b, f32x16 c) { return __builtin_amdgcn_mfma_f32_32x32x16_bf16(a, b, c, 0, 0, 0); }
; DI void attn_phase(const Params& p, unsigned char* smem) {
;     ...
;             float mx = S[0];
; #pragma unroll
;             for (int i = 1; i < 16; ++i) mx = fmaxf(mx, S[i]);
;             mx = max_x32(mx);
;             if (__any(mx > 8.0f)) {
;                 const float dm = fmaxf(mx, 0.f);
;                 const float alpha = __builtin_amdgcn_exp2f(-dm);
;                 mrun += dm;
;                 lrun *= alpha;
; #pragma unroll
;                 for (int d = 0; d < 4; ++d) O[d] = O[d] * alpha;
; #pragma unroll
;                 for (int i = 0; i < 16; ++i) { S[i] -= dm; NEGM[i] = -mrun; }
;                 if (Spend) {
; #pragma unroll
;                     for (int i = 0; i < 16; ++i) (*Spend)[i] -= dm;
;                 }
;             }
;             float ls = 0.f;
; #pragma unroll
;             for (int i = 0; i < 16; ++i) { const float e = __builtin_amdgcn_exp2f(S[i]); S[i] = e; ls += e; }
;             lrun += ls;
;             P[0] = pack8(S, 0); P[1] = pack8(S, 1);
;         };
;         auto pv_half = [&](const bf16_t* vb, int kh, int dsw, const bf16x8 (&P)[2]) __attribute__((always_inline)) {
; #pragma unroll
;             for (int s2 = 0; s2 < 2; ++s2) {
;                 const int u = kh * 2 + s2;
; #pragma unroll
;                 for (int d = 0; d < 4; ++d) {
;                     const bf16x8 A = *(const bf16x8*)(vb + (d * 32 + l31) * 64 + (((2 * u + hi) ^ dsw) * 8));
;                     O[d] = mfma32(A, P[s2], O[d]);
;                 }
;             }
;         };
.LBB0_1289:
	s_or_b64 exec, exec, s[26:27]
	v_add_f32_e32 v3, v4, v3
	v_add_f32_e32 v3, v5, v3
	v_add_f32_e32 v3, v6, v3
	v_add_f32_e32 v3, v7, v3
	v_add_f32_e32 v3, v8, v3
	v_add_f32_e32 v3, v9, v3
	v_add_f32_e32 v3, v10, v3
	v_add_f32_e32 v3, v11, v3
	v_add_f32_e32 v3, v12, v3
	v_add_f32_e32 v3, v13, v3
	v_add_f32_e32 v3, v14, v3
	v_add_f32_e32 v3, v15, v3
	v_add_f32_e32 v3, v96, v3
	v_add_f32_e32 v3, v97, v3
	v_add_f32_e32 v3, v98, v3
	v_add_f32_e32 v2, v2, v3
	v_max3_f32 v3, v112, v113, v114
	v_max3_f32 v3, v3, v115, v116
	v_max3_f32 v3, v3, v117, v118
	v_max3_f32 v3, v3, v119, v120
	v_max3_f32 v3, v3, v121, v122
	v_max3_f32 v3, v3, v123, v124
	v_max3_f32 v3, v3, v125, v126
	v_max_f32_e32 v3, v3, v127
	v_mov_b32_e32 v4, v3
	s_nop 1
	v_permlane32_swap_b32_e32 v3, v4
	v_max_f32_e32 v3, v3, v4
	v_cmp_lt_f32_e32 vcc, s42, v3
	s_cbranch_vccnz .Lattn_cold_resc1
.LBB0_1291:
	v_lshl_add_u32 v100, v189, 1, v1
	ds_read_b128 v[4:7], v100 offset:32768
	ds_read_b128 v[12:15], v100 offset:36864
	v_exp_f32_e32 v3, v112
	v_exp_f32_e32 v96, v113
	v_exp_f32_e32 v97, v114
	v_exp_f32_e32 v98, v115
	v_exp_f32_e32 v99, v116
	v_exp_f32_e32 v101, v117
	v_exp_f32_e32 v102, v118
	v_exp_f32_e32 v103, v119
	v_cvt_pk_bf16_f32 v8, v3, v96
	v_cvt_pk_bf16_f32 v9, v97, v98
	v_cvt_pk_bf16_f32 v10, v99, v101
	v_cvt_pk_bf16_f32 v11, v102, v103
	v_lshl_add_u32 v1, v190, 1, v1
	v_exp_f32_e32 v104, v120
	s_setprio 1
	s_waitcnt lgkmcnt(0)
	v_mfma_f32_32x32x16_bf16 v[64:79], v[4:7], v[8:11], v[64:79]
	ds_read_b128 v[4:7], v100 offset:40960
	v_exp_f32_e32 v105, v122
	v_exp_f32_e32 v106, v123
	v_exp_f32_e32 v107, v124
	v_exp_f32_e32 v108, v125
	v_exp_f32_e32 v109, v126
	v_exp_f32_e32 v110, v127
	v_mfma_f32_32x32x16_bf16 v[48:63], v[12:15], v[8:11], v[48:63]
	ds_read_b128 v[12:15], v100 offset:45056
	v_exp_f32_e32 v100, v121
	v_add_f32_e32 v3, v96, v3
	v_add_f32_e32 v3, v97, v3
	v_add_f32_e32 v3, v98, v3
	v_add_f32_e32 v3, v99, v3
	s_waitcnt lgkmcnt(0)
	v_mfma_f32_32x32x16_bf16 v[32:47], v[4:7], v[8:11], v[32:47]
	ds_read_b128 v[4:7], v1 offset:32768
	v_add_f32_e32 v3, v101, v3
	v_add_f32_e32 v3, v102, v3
	v_add_f32_e32 v3, v103, v3
	v_add_f32_e32 v3, v104, v3
	v_add_f32_e32 v3, v100, v3
	v_mfma_f32_32x32x16_bf16 v[16:31], v[12:15], v[8:11], v[16:31]
	ds_read_b128 v[12:15], v1 offset:36864
	v_cvt_pk_bf16_f32 v8, v104, v100
	v_cvt_pk_bf16_f32 v9, v105, v106
	v_cvt_pk_bf16_f32 v10, v107, v108
	v_cvt_pk_bf16_f32 v11, v109, v110
	s_waitcnt lgkmcnt(0)
	s_nop 0
	v_mfma_f32_32x32x16_bf16 v[64:79], v[4:7], v[8:11], v[64:79]
	ds_read_b128 v[4:7], v1 offset:40960
	v_mfma_f32_32x32x16_bf16 v[48:63], v[12:15], v[8:11], v[48:63]
	ds_read_b128 v[12:15], v1 offset:45056
	v_add_f32_e32 v1, v105, v3
	v_add_f32_e32 v1, v106, v1
	v_add_f32_e32 v1, v107, v1
	v_add_f32_e32 v1, v108, v1
	v_add_f32_e32 v1, v109, v1
	v_add_f32_e32 v1, v110, v1
	s_waitcnt lgkmcnt(0)
	v_mfma_f32_32x32x16_bf16 v[32:47], v[4:7], v[8:11], v[32:47]
	v_add_f32_e32 v2, v2, v1
	v_mfma_f32_32x32x16_bf16 v[16:31], v[12:15], v[8:11], v[16:31]
	s_setprio 0
.LBB0_1292:
	s_andn2_saveexec_b64 s[24:25], s[24:25]
	s_cbranch_execnz .Lattn_cold_half

; DI float max_x32(float x) { auto r = __builtin_amdgcn_permlane32_swap(__float_as_uint(x), __float_as_uint(x), false, false); return fmaxf(__uint_as_float(r[0]), __uint_as_float(r[1])); }
; DI void attn_phase(const Params& p, unsigned char* smem) {
;     ...
;             if (need_mask) {
; #pragma unroll
;                 for (int i = 0; i < 16; ++i) {
;                     const int key = kh * 32 + 8 * (i >> 2) + 4 * hi + (i & 3);
;                     const bool vis = (j == 0) ? (key < 16) : (kbase + key <= q0 + l31);
;                     if (!vis) S[i] = -INFINITY;
;                 }
;             }
;             float mx = S[0];
; #pragma unroll
;             for (int i = 1; i < 16; ++i) mx = fmaxf(mx, S[i]);
;             mx = max_x32(mx);
;             if (__any(mx > 8.0f)) {
;                 const float dm = fmaxf(mx, 0.f);
;                 const float alpha = __builtin_amdgcn_exp2f(-dm);
;                 mrun += dm;
;                 lrun *= alpha;
; #pragma unroll
;                 for (int d = 0; d < 4; ++d) O[d] = O[d] * alpha;
; #pragma unroll
;                 for (int i = 0; i < 16; ++i) { S[i] -= dm; NEGM[i] = -mrun; }
;                 if (Spend) {
; #pragma unroll
;                     for (int i = 0; i < 16; ++i) (*Spend)[i] -= dm;
;                 }
;             }
.Lattn_cold_mask0:
	v_add_u32_e32 v1, s47, v152
	v_subrev_u32_e32 v3, 32, v1
	v_cmp_lt_i32_e32 vcc, v3, v197
	s_nop 1
	v_cndmask_b32_e32 v97, v194, v97, vcc
	v_cmp_le_i32_e32 vcc, v3, v197
	v_subrev_u32_e32 v3, 30, v1
	s_nop 0
	v_cndmask_b32_e32 v96, v194, v96, vcc
	v_cmp_le_i32_e32 vcc, v3, v197
	v_subrev_u32_e32 v3, 29, v1
	s_nop 0
	v_cndmask_b32_e32 v98, v194, v98, vcc
	v_cmp_le_i32_e32 vcc, v3, v197
	v_subrev_u32_e32 v3, 24, v1
	s_nop 0
	v_cndmask_b32_e32 v99, v194, v99, vcc
	v_cmp_le_i32_e32 vcc, v3, v197
	v_subrev_u32_e32 v3, 23, v1
	s_nop 0
	v_cndmask_b32_e32 v100, v194, v100, vcc
	v_cmp_le_i32_e32 vcc, v3, v197
	v_subrev_u32_e32 v3, 22, v1
	s_nop 0
	v_cndmask_b32_e32 v101, v194, v101, vcc
	v_cmp_le_i32_e32 vcc, v3, v197
	v_subrev_u32_e32 v3, 21, v1
	s_nop 0
	v_cndmask_b32_e32 v102, v194, v102, vcc
	v_cmp_le_i32_e32 vcc, v3, v197
	v_add_u32_e32 v3, -16, v1
	s_nop 0
	v_cndmask_b32_e32 v103, v194, v103, vcc
	v_cmp_le_i32_e32 vcc, v3, v197
	v_add_u32_e32 v3, -15, v1
	s_nop 0
	v_cndmask_b32_e32 v104, v194, v104, vcc
	v_cmp_le_i32_e32 vcc, v3, v197
	v_add_u32_e32 v3, -14, v1
	s_nop 0
	v_cndmask_b32_e32 v105, v194, v105, vcc
	v_cmp_le_i32_e32 vcc, v3, v197
	v_add_u32_e32 v3, -13, v1
	s_nop 0
	v_cndmask_b32_e32 v106, v194, v106, vcc
	v_cmp_le_i32_e32 vcc, v3, v197
	v_add_u32_e32 v3, -8, v1
	s_nop 0
	v_cndmask_b32_e32 v107, v194, v107, vcc
	v_cmp_le_i32_e32 vcc, v3, v197
	v_add_u32_e32 v3, -7, v1
	s_nop 0
	v_cndmask_b32_e32 v108, v194, v108, vcc
	v_cmp_le_i32_e32 vcc, v3, v197
	v_add_u32_e32 v3, -6, v1
	v_add_u32_e32 v1, -5, v1
	v_cndmask_b32_e32 v109, v194, v109, vcc
	v_cmp_le_i32_e32 vcc, v3, v197
	s_nop 1
	v_cndmask_b32_e32 v110, v194, v110, vcc
	v_cmp_gt_i32_e32 vcc, v1, v197
	s_and_saveexec_b64 s[28:29], vcc
	v_mov_b32_e32 v111, s41
	s_or_b64 exec, exec, s[28:29]
	s_branch .LBB0_1283
.Lattn_cold_resc0:
	v_max_f32_e32 v1, v1, v1
	v_max_f32_e32 v4, 0, v1
	v_exp_f32_e64 v6, -v4
	v_add_f32_e32 v198, v198, v4
	v_xor_b32_e32 v80, 0x80000000, v198
	v_pk_add_f32 v[96:97], v[96:97], v[4:5] op_sel_hi:[1,0] neg_lo:[0,1] neg_hi:[0,1]
	v_pk_mul_f32 v[78:79], v[78:79], v[6:7] op_sel_hi:[1,0]
	v_pk_mul_f32 v[76:77], v[76:77], v[6:7] op_sel_hi:[1,0]
	v_pk_mul_f32 v[74:75], v[74:75], v[6:7] op_sel_hi:[1,0]
	v_pk_mul_f32 v[72:73], v[72:73], v[6:7] op_sel_hi:[1,0]
	v_pk_mul_f32 v[70:71], v[70:71], v[6:7] op_sel_hi:[1,0]
	v_pk_mul_f32 v[68:69], v[68:69], v[6:7] op_sel_hi:[1,0]
	v_pk_mul_f32 v[66:67], v[66:67], v[6:7] op_sel_hi:[1,0]
	v_pk_mul_f32 v[64:65], v[64:65], v[6:7] op_sel_hi:[1,0]
	v_pk_mul_f32 v[62:63], v[62:63], v[6:7] op_sel_hi:[1,0]
	v_pk_mul_f32 v[60:61], v[60:61], v[6:7] op_sel_hi:[1,0]
	v_pk_mul_f32 v[58:59], v[58:59], v[6:7] op_sel_hi:[1,0]
	v_pk_mul_f32 v[56:57], v[56:57], v[6:7] op_sel_hi:[1,0]
	v_pk_mul_f32 v[54:55], v[54:55], v[6:7] op_sel_hi:[1,0]
	v_pk_mul_f32 v[52:53], v[52:53], v[6:7] op_sel_hi:[1,0]
	v_pk_mul_f32 v[50:51], v[50:51], v[6:7] op_sel_hi:[1,0]
	v_pk_mul_f32 v[48:49], v[48:49], v[6:7] op_sel_hi:[1,0]
	v_pk_mul_f32 v[46:47], v[46:47], v[6:7] op_sel_hi:[1,0]
	v_pk_mul_f32 v[44:45], v[44:45], v[6:7] op_sel_hi:[1,0]
	v_pk_mul_f32 v[42:43], v[42:43], v[6:7] op_sel_hi:[1,0]
	v_pk_mul_f32 v[40:41], v[40:41], v[6:7] op_sel_hi:[1,0]
	v_pk_mul_f32 v[38:39], v[38:39], v[6:7] op_sel_hi:[1,0]
	v_pk_mul_f32 v[36:37], v[36:37], v[6:7] op_sel_hi:[1,0]
	v_pk_mul_f32 v[34:35], v[34:35], v[6:7] op_sel_hi:[1,0]
	v_pk_mul_f32 v[32:33], v[32:33], v[6:7] op_sel_hi:[1,0]
	v_pk_mul_f32 v[30:31], v[30:31], v[6:7] op_sel_hi:[1,0]
	v_pk_mul_f32 v[28:29], v[28:29], v[6:7] op_sel_hi:[1,0]
	v_pk_mul_f32 v[26:27], v[26:27], v[6:7] op_sel_hi:[1,0]
	v_pk_mul_f32 v[24:25], v[24:25], v[6:7] op_sel_hi:[1,0]
	v_pk_mul_f32 v[22:23], v[22:23], v[6:7] op_sel_hi:[1,0]
	v_pk_mul_f32 v[20:21], v[20:21], v[6:7] op_sel_hi:[1,0]
	v_pk_mul_f32 v[18:19], v[18:19], v[6:7] op_sel_hi:[1,0]
	v_pk_mul_f32 v[16:17], v[16:17], v[6:7] op_sel_hi:[1,0]
	v_pk_add_f32 v[98:99], v[98:99], v[4:5] op_sel_hi:[1,0] neg_lo:[0,1] neg_hi:[0,1]
	v_pk_add_f32 v[100:101], v[100:101], v[4:5] op_sel_hi:[1,0] neg_lo:[0,1] neg_hi:[0,1]
	v_pk_add_f32 v[102:103], v[102:103], v[4:5] op_sel_hi:[1,0] neg_lo:[0,1] neg_hi:[0,1]
	v_pk_add_f32 v[104:105], v[104:105], v[4:5] op_sel_hi:[1,0] neg_lo:[0,1] neg_hi:[0,1]
	v_pk_add_f32 v[106:107], v[106:107], v[4:5] op_sel_hi:[1,0] neg_lo:[0,1] neg_hi:[0,1]
	v_pk_add_f32 v[108:109], v[108:109], v[4:5] op_sel_hi:[1,0] neg_lo:[0,1] neg_hi:[0,1]
	v_pk_add_f32 v[110:111], v[110:111], v[4:5] op_sel_hi:[1,0] neg_lo:[0,1] neg_hi:[0,1]
	v_mul_f32_e32 v2, v2, v6
	v_sub_f32_e32 v127, v127, v4
	v_sub_f32_e32 v126, v126, v4
	v_sub_f32_e32 v125, v125, v4
	v_sub_f32_e32 v124, v124, v4
	v_sub_f32_e32 v123, v123, v4
	v_sub_f32_e32 v122, v122, v4
	v_sub_f32_e32 v121, v121, v4
	v_sub_f32_e32 v120, v120, v4
	v_sub_f32_e32 v119, v119, v4
	v_sub_f32_e32 v118, v118, v4
	v_sub_f32_e32 v117, v117, v4
	v_sub_f32_e32 v116, v116, v4
	v_sub_f32_e32 v115, v115, v4
	v_sub_f32_e32 v114, v114, v4
	v_sub_f32_e32 v113, v113, v4
	v_sub_f32_e32 v112, v112, v4
	v_mov_b32_e32 v81, v80
	v_mov_b32_e32 v82, v80
	v_mov_b32_e32 v83, v80
	v_mov_b32_e32 v84, v80
	v_mov_b32_e32 v85, v80
	v_mov_b32_e32 v86, v80
	v_mov_b32_e32 v87, v80
	v_mov_b32_e32 v88, v80
	v_mov_b32_e32 v89, v80
	v_mov_b32_e32 v90, v80
	v_mov_b32_e32 v91, v80
	v_mov_b32_e32 v92, v80
	v_mov_b32_e32 v93, v80
	v_mov_b32_e32 v94, v80
	v_mov_b32_e32 v95, v80
	s_branch .LBB0_1285
; DI float max_x32(float x) { auto r = __builtin_amdgcn_permlane32_swap(__float_as_uint(x), __float_as_uint(x), false, false); return fmaxf(__uint_as_float(r[0]), __uint_as_float(r[1])); }
; DI void attn_phase(const Params& p, unsigned char* smem) {
;     ...
;             if (need_mask) {
; #pragma unroll
;                 for (int i = 0; i < 16; ++i) {
;                     const int key = kh * 32 + 8 * (i >> 2) + 4 * hi + (i & 3);
;                     const bool vis = (j == 0) ? (key < 16) : (kbase + key <= q0 + l31);
;                     if (!vis) S[i] = -INFINITY;
;                 }
;             }
;             float mx = S[0];
; #pragma unroll
;             for (int i = 1; i < 16; ++i) mx = fmaxf(mx, S[i]);
;             mx = max_x32(mx);
;             if (__any(mx > 8.0f)) {
;                 const float dm = fmaxf(mx, 0.f);
;                 const float alpha = __builtin_amdgcn_exp2f(-dm);
;                 mrun += dm;
;                 lrun *= alpha;
; #pragma unroll
;                 for (int d = 0; d < 4; ++d) O[d] = O[d] * alpha;
; #pragma unroll
;                 for (int i = 0; i < 16; ++i) { S[i] -= dm; NEGM[i] = -mrun; }
;                 if (Spend) {
; #pragma unroll
;                     for (int i = 0; i < 16; ++i) (*Spend)[i] -= dm;
;                 }
;             }
.Lattn_cold_mask1:
	v_add_u32_e32 v99, s47, v152
	v_cmp_le_i32_e32 vcc, v99, v197
	v_add_u32_e32 v100, 1, v99
	s_nop 0
	v_cndmask_b32_e32 v112, v194, v112, vcc
	v_cmp_le_i32_e32 vcc, v100, v197
	v_add_u32_e32 v100, 2, v99
	s_nop 0
	v_cndmask_b32_e32 v113, v194, v113, vcc
	v_cmp_le_i32_e32 vcc, v100, v197
	v_add_u32_e32 v100, 3, v99
	s_nop 0
	v_cndmask_b32_e32 v114, v194, v114, vcc
	v_cmp_le_i32_e32 vcc, v100, v197
	v_add_u32_e32 v100, 8, v99
	s_nop 0
	v_cndmask_b32_e32 v115, v194, v115, vcc
	v_cmp_le_i32_e32 vcc, v100, v197
	v_add_u32_e32 v100, 9, v99
	s_nop 0
	v_cndmask_b32_e32 v116, v194, v116, vcc
	v_cmp_le_i32_e32 vcc, v100, v197
	v_add_u32_e32 v100, 10, v99
	s_nop 0
	v_cndmask_b32_e32 v117, v194, v117, vcc
	v_cmp_le_i32_e32 vcc, v100, v197
	v_add_u32_e32 v100, 11, v99
	s_nop 0
	v_cndmask_b32_e32 v118, v194, v118, vcc
	v_cmp_le_i32_e32 vcc, v100, v197
	v_add_u32_e32 v100, 16, v99
	s_nop 0
	v_cndmask_b32_e32 v119, v194, v119, vcc
	v_cmp_le_i32_e32 vcc, v100, v197
	v_add_u32_e32 v100, 17, v99
	s_nop 0
	v_cndmask_b32_e32 v120, v194, v120, vcc
	v_cmp_le_i32_e32 vcc, v100, v197
	v_add_u32_e32 v100, 18, v99
	s_nop 0
	v_cndmask_b32_e32 v121, v194, v121, vcc
	v_cmp_le_i32_e32 vcc, v100, v197
	v_add_u32_e32 v100, 19, v99
	s_nop 0
	v_cndmask_b32_e32 v122, v194, v122, vcc
	v_cmp_le_i32_e32 vcc, v100, v197
	v_add_u32_e32 v100, 24, v99
	s_nop 0
	v_cndmask_b32_e32 v123, v194, v123, vcc
	v_cmp_le_i32_e32 vcc, v100, v197
	v_add_u32_e32 v100, 25, v99
	s_nop 0
	v_cndmask_b32_e32 v124, v194, v124, vcc
	v_cmp_le_i32_e32 vcc, v100, v197
	v_add_u32_e32 v100, 26, v99
	v_add_u32_e32 v99, 27, v99
	v_cndmask_b32_e32 v125, v194, v125, vcc
	v_cmp_le_i32_e32 vcc, v100, v197
	s_nop 1
	v_cndmask_b32_e32 v126, v194, v126, vcc
	v_cmp_gt_i32_e32 vcc, v99, v197
	s_and_saveexec_b64 s[28:29], vcc
	v_mov_b32_e32 v127, s41
	s_or_b64 exec, exec, s[28:29]
	s_branch .LBB0_1289
.Lattn_cold_resc1:
	v_max_f32_e32 v3, v3, v3
	v_max_f32_e32 v4, 0, v3
	v_exp_f32_e64 v6, -v4
	v_add_f32_e32 v198, v198, v4
	v_xor_b32_e32 v80, 0x80000000, v198
	v_pk_add_f32 v[112:113], v[112:113], v[4:5] op_sel_hi:[1,0] neg_lo:[0,1] neg_hi:[0,1]
	v_mul_f32_e32 v2, v2, v6
	v_pk_mul_f32 v[78:79], v[78:79], v[6:7] op_sel_hi:[1,0]
	v_pk_mul_f32 v[76:77], v[76:77], v[6:7] op_sel_hi:[1,0]
	v_pk_mul_f32 v[74:75], v[74:75], v[6:7] op_sel_hi:[1,0]
	v_pk_mul_f32 v[72:73], v[72:73], v[6:7] op_sel_hi:[1,0]
	v_pk_mul_f32 v[70:71], v[70:71], v[6:7] op_sel_hi:[1,0]
	v_pk_mul_f32 v[68:69], v[68:69], v[6:7] op_sel_hi:[1,0]
	v_pk_mul_f32 v[66:67], v[66:67], v[6:7] op_sel_hi:[1,0]
	v_pk_mul_f32 v[64:65], v[64:65], v[6:7] op_sel_hi:[1,0]
	v_pk_mul_f32 v[62:63], v[62:63], v[6:7] op_sel_hi:[1,0]
	v_pk_mul_f32 v[60:61], v[60:61], v[6:7] op_sel_hi:[1,0]
	v_pk_mul_f32 v[58:59], v[58:59], v[6:7] op_sel_hi:[1,0]
	v_pk_mul_f32 v[56:57], v[56:57], v[6:7] op_sel_hi:[1,0]
	v_pk_mul_f32 v[54:55], v[54:55], v[6:7] op_sel_hi:[1,0]
	v_pk_mul_f32 v[52:53], v[52:53], v[6:7] op_sel_hi:[1,0]
	v_pk_mul_f32 v[50:51], v[50:51], v[6:7] op_sel_hi:[1,0]
	v_pk_mul_f32 v[48:49], v[48:49], v[6:7] op_sel_hi:[1,0]
	v_pk_mul_f32 v[46:47], v[46:47], v[6:7] op_sel_hi:[1,0]
	v_pk_mul_f32 v[44:45], v[44:45], v[6:7] op_sel_hi:[1,0]
	v_pk_mul_f32 v[42:43], v[42:43], v[6:7] op_sel_hi:[1,0]
	v_pk_mul_f32 v[40:41], v[40:41], v[6:7] op_sel_hi:[1,0]
	v_pk_mul_f32 v[38:39], v[38:39], v[6:7] op_sel_hi:[1,0]
	v_pk_mul_f32 v[36:37], v[36:37], v[6:7] op_sel_hi:[1,0]
	v_pk_mul_f32 v[34:35], v[34:35], v[6:7] op_sel_hi:[1,0]
	v_pk_mul_f32 v[32:33], v[32:33], v[6:7] op_sel_hi:[1,0]
	v_pk_mul_f32 v[30:31], v[30:31], v[6:7] op_sel_hi:[1,0]
	v_pk_mul_f32 v[28:29], v[28:29], v[6:7] op_sel_hi:[1,0]
	v_pk_mul_f32 v[26:27], v[26:27], v[6:7] op_sel_hi:[1,0]
	v_pk_mul_f32 v[24:25], v[24:25], v[6:7] op_sel_hi:[1,0]
	v_pk_mul_f32 v[22:23], v[22:23], v[6:7] op_sel_hi:[1,0]
	v_pk_mul_f32 v[20:21], v[20:21], v[6:7] op_sel_hi:[1,0]
	v_pk_mul_f32 v[18:19], v[18:19], v[6:7] op_sel_hi:[1,0]
	v_pk_mul_f32 v[16:17], v[16:17], v[6:7] op_sel_hi:[1,0]
	v_pk_add_f32 v[114:115], v[114:115], v[4:5] op_sel_hi:[1,0] neg_lo:[0,1] neg_hi:[0,1]
	v_pk_add_f32 v[116:117], v[116:117], v[4:5] op_sel_hi:[1,0] neg_lo:[0,1] neg_hi:[0,1]
	v_pk_add_f32 v[118:119], v[118:119], v[4:5] op_sel_hi:[1,0] neg_lo:[0,1] neg_hi:[0,1]
	v_pk_add_f32 v[120:121], v[120:121], v[4:5] op_sel_hi:[1,0] neg_lo:[0,1] neg_hi:[0,1]
	v_pk_add_f32 v[122:123], v[122:123], v[4:5] op_sel_hi:[1,0] neg_lo:[0,1] neg_hi:[0,1]
	v_pk_add_f32 v[124:125], v[124:125], v[4:5] op_sel_hi:[1,0] neg_lo:[0,1] neg_hi:[0,1]
	v_pk_add_f32 v[126:127], v[126:127], v[4:5] op_sel_hi:[1,0] neg_lo:[0,1] neg_hi:[0,1]
	v_mov_b32_e32 v81, v80
	v_mov_b32_e32 v82, v80
	v_mov_b32_e32 v83, v80
	v_mov_b32_e32 v84, v80
	v_mov_b32_e32 v85, v80
	v_mov_b32_e32 v86, v80
	v_mov_b32_e32 v87, v80
	v_mov_b32_e32 v88, v80
	v_mov_b32_e32 v89, v80
	v_mov_b32_e32 v90, v80
	v_mov_b32_e32 v91, v80
	v_mov_b32_e32 v92, v80
	v_mov_b32_e32 v93, v80
	v_mov_b32_e32 v94, v80
	v_mov_b32_e32 v95, v80
	s_branch .LBB0_1291
; DI void attn_phase(const Params& p, unsigned char* smem) {
;     ...
;             if (need_mask) {
; #pragma unroll
;                 for (int i = 0; i < 16; ++i) {
;                     const int key = kh * 32 + 8 * (i >> 2) + 4 * hi + (i & 3);
;                     const bool vis = (j == 0) ? (key < 16) : (kbase + key <= q0 + l31);
;                     if (!vis) S[i] = -INFINITY;
;                 }
;     ...
;                 } else {
;                     softmax_half(S0, nullptr, j, 0, kbase, need_mask, P);
;                     pv_half(vb, 0, dsw, P);
.Lattn_cold_half:
	s_and_saveexec_b64 s[26:27], s[22:23]
	s_cbranch_execz .LBB0_1297
	v_add_u32_e32 v1, s47, v152
	v_subrev_u32_e32 v3, 32, v1
	v_cmp_le_i32_e32 vcc, v3, v197
	s_or_b64 vcc, s[20:21], vcc
	v_subrev_u32_e32 v4, 29, v1
	v_cndmask_b32_e32 v96, v194, v96, vcc
	v_cmp_lt_i32_e32 vcc, v3, v197
	s_or_b64 vcc, s[20:21], vcc
	v_subrev_u32_e32 v3, 30, v1
	v_cndmask_b32_e32 v97, v194, v97, vcc
	v_cmp_le_i32_e32 vcc, v3, v197
	s_or_b64 vcc, s[20:21], vcc
	v_subrev_u32_e32 v5, 24, v1
	v_cndmask_b32_e32 v3, v194, v98, vcc
	v_cmp_le_i32_e32 vcc, v4, v197
	s_or_b64 vcc, s[20:21], vcc
	v_subrev_u32_e32 v6, 23, v1
	v_cndmask_b32_e32 v4, v194, v99, vcc
	v_cmp_le_i32_e32 vcc, v5, v197
	s_or_b64 vcc, s[20:21], vcc
	v_subrev_u32_e32 v7, 22, v1
	v_cndmask_b32_e32 v5, v194, v100, vcc
	v_cmp_le_i32_e32 vcc, v6, v197
	s_or_b64 vcc, s[20:21], vcc
	v_subrev_u32_e32 v8, 21, v1
	v_cndmask_b32_e32 v6, v194, v101, vcc
	v_cmp_le_i32_e32 vcc, v7, v197
	s_or_b64 vcc, s[20:21], vcc
	v_add_u32_e32 v9, -16, v1
	v_cndmask_b32_e32 v7, v194, v102, vcc
	v_cmp_le_i32_e32 vcc, v8, v197
	s_or_b64 vcc, s[20:21], vcc
	s_nop 0
	v_cndmask_b32_e32 v8, v194, v103, vcc
	v_cmp_gt_i32_e32 vcc, v9, v197
	s_or_b64 vcc, s[20:21], vcc
	s_nop 0
	v_cndmask_b32_e32 v98, v98, v3, vcc
	v_add_u32_e32 v3, -15, v1
	v_cndmask_b32_e32 v103, v103, v8, vcc
	v_cndmask_b32_e32 v102, v102, v7, vcc
	v_cndmask_b32_e32 v101, v101, v6, vcc
	v_cndmask_b32_e32 v100, v100, v5, vcc
	v_cndmask_b32_e32 v99, v99, v4, vcc
	v_cndmask_b32_e32 v104, v104, v194, vcc
	v_cmp_gt_i32_e32 vcc, v3, v197
	s_or_b64 vcc, s[20:21], vcc
	v_add_u32_e32 v3, -14, v1
	v_cndmask_b32_e32 v105, v105, v194, vcc
	v_cmp_gt_i32_e32 vcc, v3, v197
	s_or_b64 vcc, s[20:21], vcc
	v_add_u32_e32 v3, -13, v1
	v_cndmask_b32_e32 v106, v106, v194, vcc
	v_cmp_gt_i32_e32 vcc, v3, v197
	s_or_b64 vcc, s[20:21], vcc
	v_add_u32_e32 v3, -8, v1
	v_cndmask_b32_e32 v107, v107, v194, vcc
	v_cmp_gt_i32_e32 vcc, v3, v197
	s_or_b64 vcc, s[20:21], vcc
	v_add_u32_e32 v3, -7, v1
	v_cndmask_b32_e32 v108, v108, v194, vcc
	v_cmp_gt_i32_e32 vcc, v3, v197
	s_or_b64 vcc, s[20:21], vcc
	v_add_u32_e32 v3, -6, v1
	v_cndmask_b32_e32 v109, v109, v194, vcc
	v_cmp_gt_i32_e32 vcc, v3, v197
	s_or_b64 vcc, s[20:21], vcc
	v_add_u32_e32 v1, -5, v1
	v_cndmask_b32_e32 v110, v110, v194, vcc
	v_cmp_gt_i32_e32 vcc, v1, v197
	s_or_b64 s[22:23], s[20:21], vcc
	s_and_saveexec_b64 s[20:21], s[22:23]
	v_mov_b32_e32 v111, s41
	s_or_b64 exec, exec, s[20:21]
; DI float max_x32(float x) { auto r = __builtin_amdgcn_permlane32_swap(__float_as_uint(x), __float_as_uint(x), false, false); return fmaxf(__uint_as_float(r[0]), __uint_as_float(r[1])); }
; DI f32x16 mfma32(bf16x8 a, bf16x8 b, f32x16 c) { return __builtin_amdgcn_mfma_f32_32x32x16_bf16(a, b, c, 0, 0, 0); }
; DI void attn_phase(const Params& p, unsigned char* smem) {
;     ...
;             float mx = S[0];
; #pragma unroll
;             for (int i = 1; i < 16; ++i) mx = fmaxf(mx, S[i]);
;             mx = max_x32(mx);
;             if (__any(mx > 8.0f)) {
;                 const float dm = fmaxf(mx, 0.f);
;                 const float alpha = __builtin_amdgcn_exp2f(-dm);
;                 mrun += dm;
;                 lrun *= alpha;
; #pragma unroll
;                 for (int d = 0; d < 4; ++d) O[d] = O[d] * alpha;
; #pragma unroll
;                 for (int i = 0; i < 16; ++i) { S[i] -= dm; NEGM[i] = -mrun; }
;                 if (Spend) {
; #pragma unroll
;                     for (int i = 0; i < 16; ++i) (*Spend)[i] -= dm;
;                 }
;             }
;             float ls = 0.f;
; #pragma unroll
;             for (int i = 0; i < 16; ++i) { const float e = __builtin_amdgcn_exp2f(S[i]); S[i] = e; ls += e; }
;             lrun += ls;
;             P[0] = pack8(S, 0); P[1] = pack8(S, 1);
;         };
;         auto pv_half = [&](const bf16_t* vb, int kh, int dsw, const bf16x8 (&P)[2]) __attribute__((always_inline)) {
; #pragma unroll
;             for (int s2 = 0; s2 < 2; ++s2) {
;                 const int u = kh * 2 + s2;
; #pragma unroll
;                 for (int d = 0; d < 4; ++d) {
;                     const bf16x8 A = *(const bf16x8*)(vb + (d * 32 + l31) * 64 + (((2 * u + hi) ^ dsw) * 8));
;                     O[d] = mfma32(A, P[s2], O[d]);
;                 }
;             }
;         };
.LBB0_1297:
	s_or_b64 exec, exec, s[26:27]
	s_nop 3
	v_max3_f32 v1, v96, v97, v98
	v_max3_f32 v1, v1, v99, v100
	v_max3_f32 v1, v1, v101, v102
	v_max3_f32 v1, v1, v103, v104
	v_max3_f32 v1, v1, v105, v106
	v_max3_f32 v1, v1, v107, v108
	v_max3_f32 v1, v1, v109, v110
	v_max_f32_e32 v1, v1, v111
	v_mov_b32_e32 v3, v1
	s_nop 1
	v_permlane32_swap_b32_e32 v1, v3
	v_max_f32_e32 v1, v1, v3
	v_cmp_lt_f32_e32 vcc, s42, v1
	s_cbranch_vccz .LBB0_1299
	v_max_f32_e32 v1, v1, v1
	v_max_f32_e32 v4, 0, v1
	v_exp_f32_e64 v6, -v4
	v_add_f32_e32 v198, v198, v4
	v_xor_b32_e32 v80, 0x80000000, v198
	v_pk_add_f32 v[96:97], v[96:97], v[4:5] op_sel_hi:[1,0] neg_lo:[0,1] neg_hi:[0,1]
	v_mul_f32_e32 v2, v2, v6
	v_pk_mul_f32 v[78:79], v[78:79], v[6:7] op_sel_hi:[1,0]
	v_pk_mul_f32 v[76:77], v[76:77], v[6:7] op_sel_hi:[1,0]
	v_pk_mul_f32 v[74:75], v[74:75], v[6:7] op_sel_hi:[1,0]
	v_pk_mul_f32 v[72:73], v[72:73], v[6:7] op_sel_hi:[1,0]
	v_pk_mul_f32 v[70:71], v[70:71], v[6:7] op_sel_hi:[1,0]
	v_pk_mul_f32 v[68:69], v[68:69], v[6:7] op_sel_hi:[1,0]
	v_pk_mul_f32 v[66:67], v[66:67], v[6:7] op_sel_hi:[1,0]
	v_pk_mul_f32 v[64:65], v[64:65], v[6:7] op_sel_hi:[1,0]
	v_pk_mul_f32 v[62:63], v[62:63], v[6:7] op_sel_hi:[1,0]
	v_pk_mul_f32 v[60:61], v[60:61], v[6:7] op_sel_hi:[1,0]
	v_pk_mul_f32 v[58:59], v[58:59], v[6:7] op_sel_hi:[1,0]
	v_pk_mul_f32 v[56:57], v[56:57], v[6:7] op_sel_hi:[1,0]
	v_pk_mul_f32 v[54:55], v[54:55], v[6:7] op_sel_hi:[1,0]
	v_pk_mul_f32 v[52:53], v[52:53], v[6:7] op_sel_hi:[1,0]
	v_pk_mul_f32 v[50:51], v[50:51], v[6:7] op_sel_hi:[1,0]
	v_pk_mul_f32 v[48:49], v[48:49], v[6:7] op_sel_hi:[1,0]
	v_pk_mul_f32 v[46:47], v[46:47], v[6:7] op_sel_hi:[1,0]
	v_pk_mul_f32 v[44:45], v[44:45], v[6:7] op_sel_hi:[1,0]
	v_pk_mul_f32 v[42:43], v[42:43], v[6:7] op_sel_hi:[1,0]
	v_pk_mul_f32 v[40:41], v[40:41], v[6:7] op_sel_hi:[1,0]
	v_pk_mul_f32 v[38:39], v[38:39], v[6:7] op_sel_hi:[1,0]
	v_pk_mul_f32 v[36:37], v[36:37], v[6:7] op_sel_hi:[1,0]
	v_pk_mul_f32 v[34:35], v[34:35], v[6:7] op_sel_hi:[1,0]
	v_pk_mul_f32 v[32:33], v[32:33], v[6:7] op_sel_hi:[1,0]
	v_pk_mul_f32 v[30:31], v[30:31], v[6:7] op_sel_hi:[1,0]
	v_pk_mul_f32 v[28:29], v[28:29], v[6:7] op_sel_hi:[1,0]
	v_pk_mul_f32 v[26:27], v[26:27], v[6:7] op_sel_hi:[1,0]
	v_pk_mul_f32 v[24:25], v[24:25], v[6:7] op_sel_hi:[1,0]
	v_pk_mul_f32 v[22:23], v[22:23], v[6:7] op_sel_hi:[1,0]
	v_pk_mul_f32 v[20:21], v[20:21], v[6:7] op_sel_hi:[1,0]
	v_pk_mul_f32 v[18:19], v[18:19], v[6:7] op_sel_hi:[1,0]
	v_pk_mul_f32 v[16:17], v[16:17], v[6:7] op_sel_hi:[1,0]
	v_pk_add_f32 v[98:99], v[98:99], v[4:5] op_sel_hi:[1,0] neg_lo:[0,1] neg_hi:[0,1]
	v_pk_add_f32 v[100:101], v[100:101], v[4:5] op_sel_hi:[1,0] neg_lo:[0,1] neg_hi:[0,1]
	v_pk_add_f32 v[102:103], v[102:103], v[4:5] op_sel_hi:[1,0] neg_lo:[0,1] neg_hi:[0,1]
	v_pk_add_f32 v[104:105], v[104:105], v[4:5] op_sel_hi:[1,0] neg_lo:[0,1] neg_hi:[0,1]
	v_pk_add_f32 v[106:107], v[106:107], v[4:5] op_sel_hi:[1,0] neg_lo:[0,1] neg_hi:[0,1]
	v_pk_add_f32 v[108:109], v[108:109], v[4:5] op_sel_hi:[1,0] neg_lo:[0,1] neg_hi:[0,1]
	v_pk_add_f32 v[110:111], v[110:111], v[4:5] op_sel_hi:[1,0] neg_lo:[0,1] neg_hi:[0,1]
	v_mov_b32_e32 v81, v80
	v_mov_b32_e32 v82, v80
	v_mov_b32_e32 v83, v80
	v_mov_b32_e32 v84, v80
	v_mov_b32_e32 v85, v80
	v_mov_b32_e32 v86, v80
	v_mov_b32_e32 v87, v80
	v_mov_b32_e32 v88, v80
	v_mov_b32_e32 v89, v80
	v_mov_b32_e32 v90, v80
	v_mov_b32_e32 v91, v80
	v_mov_b32_e32 v92, v80
	v_mov_b32_e32 v93, v80
	v_mov_b32_e32 v94, v80
	v_mov_b32_e32 v95, v80
.LBB0_1299:
	v_exp_f32_e32 v3, v97
	v_exp_f32_e32 v97, v99
	v_lshl_add_u32 v99, v186, 1, s49
	v_exp_f32_e32 v1, v96
	v_exp_f32_e32 v96, v98
	v_exp_f32_e32 v98, v100
	v_lshl_add_u32 v100, v187, 1, v99
	ds_read_b128 v[4:7], v100 offset:32768
	ds_read_b128 v[12:15], v100 offset:36864
	v_exp_f32_e32 v101, v101
	v_exp_f32_e32 v102, v102
	v_exp_f32_e32 v103, v103
	v_cvt_pk_bf16_f32 v8, v1, v3
	v_cvt_pk_bf16_f32 v9, v96, v97
	v_cvt_pk_bf16_f32 v10, v98, v101
	v_cvt_pk_bf16_f32 v11, v102, v103
	v_lshl_add_u32 v99, v188, 1, v99
	v_exp_f32_e32 v104, v104
	s_waitcnt lgkmcnt(0)
	v_mfma_f32_32x32x16_bf16 v[64:79], v[4:7], v[8:11], v[64:79]
	ds_read_b128 v[4:7], v100 offset:40960
	v_add_f32_e32 v1, 0, v1
	v_add_f32_e32 v1, v3, v1
	v_add_f32_e32 v1, v96, v1
	v_add_f32_e32 v1, v97, v1
	v_add_f32_e32 v1, v98, v1
	v_add_f32_e32 v1, v101, v1
	v_mfma_f32_32x32x16_bf16 v[48:63], v[12:15], v[8:11], v[48:63]
	ds_read_b128 v[12:15], v100 offset:45056
	v_exp_f32_e32 v100, v105
	v_exp_f32_e32 v105, v106
	v_exp_f32_e32 v106, v107
	v_exp_f32_e32 v107, v108
	v_exp_f32_e32 v108, v109
	v_exp_f32_e32 v109, v110
	s_waitcnt lgkmcnt(0)
	v_mfma_f32_32x32x16_bf16 v[32:47], v[4:7], v[8:11], v[32:47]
	ds_read_b128 v[4:7], v99 offset:32768
	v_exp_f32_e32 v110, v111
	v_add_f32_e32 v1, v102, v1
	v_add_f32_e32 v1, v103, v1
	v_add_f32_e32 v1, v104, v1
	v_add_f32_e32 v1, v100, v1
	v_add_f32_e32 v1, v105, v1
	v_mfma_f32_32x32x16_bf16 v[16:31], v[12:15], v[8:11], v[16:31]
	ds_read_b128 v[12:15], v99 offset:36864
	v_cvt_pk_bf16_f32 v8, v104, v100
	v_cvt_pk_bf16_f32 v9, v105, v106
	v_cvt_pk_bf16_f32 v10, v107, v108
	v_cvt_pk_bf16_f32 v11, v109, v110
	v_add_f32_e32 v1, v106, v1
	v_add_f32_e32 v1, v107, v1
	s_waitcnt lgkmcnt(0)
	v_mfma_f32_32x32x16_bf16 v[64:79], v[4:7], v[8:11], v[64:79]
	ds_read_b128 v[4:7], v99 offset:40960
	v_add_f32_e32 v1, v108, v1
	v_add_f32_e32 v1, v109, v1
	v_add_f32_e32 v1, v110, v1
	v_add_f32_e32 v2, v2, v1
	v_mfma_f32_32x32x16_bf16 v[48:63], v[12:15], v[8:11], v[48:63]
	ds_read_b128 v[12:15], v99 offset:45056
	s_waitcnt lgkmcnt(0)
	v_mfma_f32_32x32x16_bf16 v[32:47], v[4:7], v[8:11], v[32:47]
	v_mfma_f32_32x32x16_bf16 v[16:31], v[12:15], v[8:11], v[16:31]
	s_branch .LBB0_1300
